# Hyena filter-gen loop: the three later H3 row loads issued before the LDS weight reads (LDS dest renamed)
# speedup vs baseline: 1.0022x; 1.0022x over previous
.LBB0_310:
	global_load_dwordx4 v[204:207], v[154:155], off
	v_add_co_u32_e32 v246, vcc, 0x20000, v154
	s_nop 1
	v_addc_co_u32_e32 v247, vcc, 0, v155, vcc
	v_add_co_u32_e32 v248, vcc, 0x40000, v154
	s_nop 1
	v_addc_co_u32_e32 v249, vcc, 0, v155, vcc
	v_add_co_u32_e32 v250, vcc, 0x60000, v154
	s_nop 1
	v_addc_co_u32_e32 v251, vcc, 0, v155, vcc
	global_load_dwordx4 v[230:233], v[246:247], off
	global_load_dwordx4 v[234:237], v[248:249], off
	global_load_dwordx4 v[238:241], v[250:251], off
	v_mov_b32_e32 v86, s52
	ds_read_b128 v[226:229], v86
	ds_read_b128 v[246:249], v86 offset:256
	s_mov_b32 s53, 0x20000
	s_add_i32 s50, s50, 4
	s_add_i32 s52, s52, 16
	s_waitcnt lgkmcnt(1)
	v_mov_b32_e32 v157, v227
	s_waitcnt lgkmcnt(0)
	v_mov_b32_e32 v156, v246
	v_mov_b32_e32 v242, v248
	v_mov_b32_e32 v243, v229
	v_mov_b32_e32 v227, v247
	v_mov_b32_e32 v229, v249
	s_cmp_lt_u32 s50, 60
	s_waitcnt vmcnt(3)
	v_pk_mul_f32 v[208:209], v[204:205], v[156:157]
	v_pk_mul_f32 v[252:253], v[206:207], v[242:243]
	v_pk_fma_f32 v[208:209], v[204:205], v[226:227], v[208:209] op_sel:[0,0,1] op_sel_hi:[1,1,0]
	v_pk_fma_f32 v[252:253], v[206:207], v[228:229], v[252:253] op_sel:[0,0,1] op_sel_hi:[1,1,0]
	s_nop 0
	v_pk_add_f32 v[208:209], v[208:209], v[252:253]
	s_nop 0
	v_pk_add_f32 v[150:151], v[150:151], v[208:209]
	s_waitcnt vmcnt(2)
	v_pk_mul_f32 v[208:209], v[230:231], v[156:157]
	v_pk_mul_f32 v[252:253], v[232:233], v[242:243]
	v_pk_fma_f32 v[208:209], v[230:231], v[226:227], v[208:209] op_sel:[0,0,1] op_sel_hi:[1,1,0]
	v_pk_fma_f32 v[252:253], v[232:233], v[228:229], v[252:253] op_sel:[0,0,1] op_sel_hi:[1,1,0]
	s_nop 0
	v_pk_add_f32 v[208:209], v[208:209], v[252:253]
	s_nop 0
	v_pk_add_f32 v[146:147], v[146:147], v[208:209]
	s_waitcnt vmcnt(1)
	v_pk_mul_f32 v[208:209], v[234:235], v[156:157]
	v_pk_mul_f32 v[252:253], v[236:237], v[242:243]
	v_pk_fma_f32 v[208:209], v[234:235], v[226:227], v[208:209] op_sel:[0,0,1] op_sel_hi:[1,1,0]
	v_pk_fma_f32 v[252:253], v[236:237], v[228:229], v[252:253] op_sel:[0,0,1] op_sel_hi:[1,1,0]
	s_nop 0
	v_pk_add_f32 v[208:209], v[208:209], v[252:253]
	s_nop 0
	v_pk_add_f32 v[142:143], v[142:143], v[208:209]
	v_lshl_add_u64 v[154:155], v[154:155], 0, 16
	s_waitcnt vmcnt(0)
	v_pk_mul_f32 v[156:157], v[238:239], v[156:157]
	v_pk_mul_f32 v[208:209], v[240:241], v[242:243]
	v_pk_fma_f32 v[156:157], v[238:239], v[226:227], v[156:157] op_sel:[0,0,1] op_sel_hi:[1,1,0]
	v_pk_fma_f32 v[208:209], v[240:241], v[228:229], v[208:209] op_sel:[0,0,1] op_sel_hi:[1,1,0]
	ds_read_b128 v[226:229], v86 offset:512
	ds_read_b128 v[242:245], v86 offset:768
	v_pk_add_f32 v[156:157], v[156:157], v[208:209]
	s_nop 0
	v_pk_add_f32 v[138:139], v[138:139], v[156:157]
	s_waitcnt lgkmcnt(1)
	v_mov_b32_e32 v157, v227
	s_waitcnt lgkmcnt(0)
	v_mov_b32_e32 v156, v242
	v_pk_mul_f32 v[208:209], v[204:205], v[156:157]
	v_mov_b32_e32 v227, v243
	v_pk_fma_f32 v[204:205], v[204:205], v[226:227], v[208:209] op_sel:[0,0,1] op_sel_hi:[1,1,0]
	v_mov_b32_e32 v208, v244
	v_mov_b32_e32 v209, v229
	v_pk_mul_f32 v[242:243], v[206:207], v[208:209]
	v_mov_b32_e32 v229, v245
	v_pk_fma_f32 v[206:207], v[206:207], v[228:229], v[242:243] op_sel:[0,0,1] op_sel_hi:[1,1,0]
	s_nop 0
	v_pk_add_f32 v[204:205], v[204:205], v[206:207]
	v_pk_mul_f32 v[206:207], v[232:233], v[208:209]
	v_pk_add_f32 v[152:153], v[152:153], v[204:205]
	v_pk_mul_f32 v[204:205], v[230:231], v[156:157]
	v_pk_fma_f32 v[206:207], v[232:233], v[228:229], v[206:207] op_sel:[0,0,1] op_sel_hi:[1,1,0]
	v_pk_fma_f32 v[204:205], v[230:231], v[226:227], v[204:205] op_sel:[0,0,1] op_sel_hi:[1,1,0]
	s_nop 0
	v_pk_add_f32 v[204:205], v[204:205], v[206:207]
	v_pk_mul_f32 v[206:207], v[236:237], v[208:209]
	v_pk_add_f32 v[148:149], v[148:149], v[204:205]
	v_pk_mul_f32 v[204:205], v[234:235], v[156:157]
	v_pk_fma_f32 v[206:207], v[236:237], v[228:229], v[206:207] op_sel:[0,0,1] op_sel_hi:[1,1,0]
	v_pk_fma_f32 v[204:205], v[234:235], v[226:227], v[204:205] op_sel:[0,0,1] op_sel_hi:[1,1,0]
	v_pk_mul_f32 v[156:157], v[238:239], v[156:157]
	v_pk_add_f32 v[204:205], v[204:205], v[206:207]
	v_pk_fma_f32 v[156:157], v[238:239], v[226:227], v[156:157] op_sel:[0,0,1] op_sel_hi:[1,1,0]
	v_pk_add_f32 v[144:145], v[144:145], v[204:205]
	v_pk_mul_f32 v[204:205], v[240:241], v[208:209]
	s_nop 0
	v_pk_fma_f32 v[204:205], v[240:241], v[228:229], v[204:205] op_sel:[0,0,1] op_sel_hi:[1,1,0]
	s_nop 0
	v_pk_add_f32 v[156:157], v[156:157], v[204:205]
	s_nop 0
	v_pk_add_f32 v[140:141], v[140:141], v[156:157]
	s_cbranch_scc1 .LBB0_310
	v_or_b32_e32 v154, s47, v164
	v_cvt_f32_u32_e32 v86, v154
	v_div_scale_f32 v155, s[52:53], s57, s57, v86
	v_rcp_f32_e32 v156, v155
	v_div_scale_f32 v157, vcc, v86, s57, v86
	v_fma_f32 v204, -v155, v156, 1.0
	v_fmac_f32_e32 v156, v204, v156
	v_mul_f32_e32 v204, v157, v156
	v_fma_f32 v205, -v155, v204, v157
	v_fmac_f32_e32 v204, v205, v156
	v_fma_f32 v155, -v155, v204, v157
	v_div_fmas_f32 v155, v155, v156, v204
	v_div_fixup_f32 v86, v155, s57, v86
	v_mul_f32_e64 v86, |v203|, v86
	v_mul_f32_e32 v155, 0x3fb8aa3b, v86
	v_fma_f32 v156, v86, s58, -v155
	v_rndne_f32_e32 v157, v155
	v_fmac_f32_e32 v156, 0x32a5705f, v86
	v_sub_f32_e32 v155, v155, v157
	v_add_f32_e32 v155, v155, v156
	v_cvt_i32_f32_e32 v156, v157
	v_exp_f32_e32 v155, v155
	v_cmp_ngt_f32_e32 vcc, s59, v86
	v_ldexp_f32 v155, v155, v156
	s_nop 0
	v_cndmask_b32_e32 v155, 0, v155, vcc
	v_cmp_nlt_f32_e32 vcc, s60, v86
	s_nop 1
	v_cndmask_b32_e32 v155, v200, v155, vcc
	v_mul_f32_e32 v86, v155, v150
	v_mul_f32_e32 v156, v155, v151
	v_mul_f32_e32 v152, v155, v152
	v_mul_f32_e32 v153, v155, v153
	v_cmp_ne_u32_e32 vcc, 0, v154
	s_and_saveexec_b64 s[52:53], vcc
	s_xor_b64 s[52:53], exec, s[52:53]
	s_cbranch_execz .LBB0_313
	v_lshl_add_u32 v150, v154, 3, 0
	ds_write_b64 v150, v[86:87]
	v_sub_u32_e32 v86, 0x2000, v154
	v_mov_b32_e32 v155, v87
	v_lshl_add_u32 v150, v86, 3, 0
	v_mov_b32_e32 v157, v87
	ds_write_b64 v150, v[156:157]
	v_lshl_add_u64 v[150:151], v[154:155], 2, s[80:81]
	v_lshlrev_b32_e32 v86, 2, v86
	global_store_dword v[150:151], v152, off
	global_store_dword v86, v153, s[80:81]
	v_mov_b64_e32 v[150:151], v[154:155]
